# v35 + ya_unit: one batch of 30 cache-warming loads at unit start so its serialized exec-masked loads hit cache
# speedup vs baseline: 1.0013x; 1.0013x over previous
.LBB0_127:
	v_mov_b32_e32 v26, v243
	s_load_dwordx2 s[6:7], s[58:59], 0x38
	v_lshlrev_b32_e32 v0, 3, v26
	v_and_b32_e32 v28, 0x1f8, v0
	v_lshlrev_b32_e32 v0, 2, v28
	s_mov_b64 s[8:9], 0x1000
	s_waitcnt lgkmcnt(0)
	s_add_u32 s6, s6, s10
	s_addc_u32 s7, s7, s1
	v_lshl_add_u64 v[18:19], s[6:7], 0, v[0:1]
	v_lshl_add_u64 v[20:21], v[18:19], 0, s[8:9]
	global_load_dwordx4 v[2:5], v0, s[6:7] offset:16
	global_load_dwordx4 v[6:9], v0, s[6:7]
	global_load_dwordx4 v[10:13], v0, s[6:7] offset:2064
	global_load_dwordx4 v[14:17], v0, s[6:7] offset:2048
	v_add_co_u32_e32 v18, vcc, s75, v18
	v_ashrrev_i32_e32 v0, 3, v26
	s_nop 0
	v_addc_co_u32_e32 v19, vcc, 0, v19, vcc
	global_load_dwordx4 v[22:25], v[18:19], off
	s_nop 0
	global_load_dwordx4 v[18:21], v[20:21], off offset:16
	v_and_b32_e32 v0, -8, v0
	v_add_u32_e32 v26, s11, v0
	v_add_u32_e32 v72, -2, v26
	v_max_i32_e32 v72, 0, v72
	v_mul_lo_u32 v72, v72, s47
	v_lshl_add_u32 v72, v28, 1, v72
	global_load_dwordx4 v[76:79], v72, s[2:3]
	global_load_dwordx4 v[76:79], v72, s[2:3] offset:1024
	global_load_dwordx4 v[76:79], v72, s[2:3] offset:2048
	v_add_u32_e32 v72, 0x1400, v72
	global_load_dwordx4 v[76:79], v72, s[2:3]
	global_load_dwordx4 v[76:79], v72, s[2:3] offset:1024
	global_load_dwordx4 v[76:79], v72, s[2:3] offset:2048
	v_add_u32_e32 v72, 0x1400, v72
	global_load_dwordx4 v[76:79], v72, s[2:3]
	global_load_dwordx4 v[76:79], v72, s[2:3] offset:1024
	global_load_dwordx4 v[76:79], v72, s[2:3] offset:2048
	v_add_u32_e32 v72, 0x1400, v72
	global_load_dwordx4 v[76:79], v72, s[2:3]
	global_load_dwordx4 v[76:79], v72, s[2:3] offset:1024
	global_load_dwordx4 v[76:79], v72, s[2:3] offset:2048
	v_add_u32_e32 v72, 0x1400, v72
	global_load_dwordx4 v[76:79], v72, s[2:3]
	global_load_dwordx4 v[76:79], v72, s[2:3] offset:1024
	global_load_dwordx4 v[76:79], v72, s[2:3] offset:2048
	v_add_u32_e32 v72, 0x1400, v72
	global_load_dwordx4 v[76:79], v72, s[2:3]
	global_load_dwordx4 v[76:79], v72, s[2:3] offset:1024
	global_load_dwordx4 v[76:79], v72, s[2:3] offset:2048
	v_add_u32_e32 v72, 0x1400, v72
	global_load_dwordx4 v[76:79], v72, s[2:3]
	global_load_dwordx4 v[76:79], v72, s[2:3] offset:1024
	global_load_dwordx4 v[76:79], v72, s[2:3] offset:2048
	v_add_u32_e32 v72, 0x1400, v72
	global_load_dwordx4 v[76:79], v72, s[2:3]
	global_load_dwordx4 v[76:79], v72, s[2:3] offset:1024
	global_load_dwordx4 v[76:79], v72, s[2:3] offset:2048
	v_add_u32_e32 v72, 0x1400, v72
	global_load_dwordx4 v[76:79], v72, s[2:3]
	global_load_dwordx4 v[76:79], v72, s[2:3] offset:1024
	global_load_dwordx4 v[76:79], v72, s[2:3] offset:2048
	v_add_u32_e32 v72, 0x1400, v72
	global_load_dwordx4 v[76:79], v72, s[2:3]
	global_load_dwordx4 v[76:79], v72, s[2:3] offset:1024
	global_load_dwordx4 v[76:79], v72, s[2:3] offset:2048
	s_movk_i32 s6, 0xff8
	v_add_u32_e32 v27, -2, v26
	v_and_or_b32 v60, v26, s6, 7
	v_and_b32_e32 v0, 0xffe, v27
	v_cmp_lt_i32_e32 vcc, 1, v26
	v_cmp_le_u32_e64 s[38:39], v0, v60
	s_and_b64 s[8:9], vcc, s[38:39]
	v_mov_b32_e32 v40, 0
	v_lshlrev_b32_e32 v0, 1, v28
	v_mov_b32_e32 v56, 0
	v_mov_b32_e32 v57, 0
	v_mov_b32_e32 v48, 0
	v_mov_b32_e32 v49, 0
	v_mov_b32_e32 v42, 0
	v_mov_b32_e32 v43, 0
	v_mov_b32_e32 v36, 0
	v_mov_b32_e32 v37, 0
	s_and_saveexec_b64 s[6:7], s[8:9]
	s_cbranch_execz .LBB0_129
	v_mov_b64_e32 v[28:29], s[2:3]
	v_mad_u64_u32 v[28:29], s[8:9], v27, s47, v[28:29]
	v_lshl_add_u64 v[32:33], v[28:29], 0, v[0:1]
	global_load_dwordx4 v[28:31], v[32:33], off offset:1024
	s_nop 0
	global_load_dwordx4 v[32:35], v[32:33], off offset:2048
	s_waitcnt vmcnt(1)
	v_lshlrev_b32_e32 v38, 16, v28
	v_and_b32_e32 v39, 0xffff0000, v28
	s_waitcnt vmcnt(0)
	v_lshlrev_b32_e32 v44, 16, v32
	v_and_b32_e32 v45, 0xffff0000, v32
	v_lshlrev_b32_e32 v28, 16, v29
	v_and_b32_e32 v29, 0xffff0000, v29
	v_lshlrev_b32_e32 v32, 16, v33
	v_and_b32_e32 v33, 0xffff0000, v33
	v_lshlrev_b32_e32 v42, 16, v30
	v_and_b32_e32 v43, 0xffff0000, v30
	v_lshlrev_b32_e32 v46, 16, v34
	v_and_b32_e32 v47, 0xffff0000, v34
	v_lshlrev_b32_e32 v30, 16, v31
	v_lshlrev_b32_e32 v34, 16, v35
	v_and_b32_e32 v35, 0xffff0000, v35
	v_and_b32_e32 v31, 0xffff0000, v31
	v_pk_mul_f32 v[36:37], v[30:31], v[34:35]
	v_pk_mul_f32 v[48:49], v[28:29], v[32:33]
	v_pk_mul_f32 v[42:43], v[42:43], v[46:47]
	v_pk_mul_f32 v[56:57], v[38:39], v[44:45]
